# epilogue gate-load prefetch (mem+diff units), saddr-form K/V DMA, rotated P.V reads with the wave's own exp/row-sum VALU placed in the MFMA gaps
# speedup vs baseline: 1.0154x; 1.0016x over previous
; #define SBAR() __builtin_amdgcn_sched_barrier(0)
; #define STAGE(t) do { const char* kt_ = Pk + (size_t)((t) * KVBLK) * (INC * 2); const int so_ = ((t) & 3) * SHM_K; \
;     GLDS(kt_ + koff, ldsA + 4 * SHM_V + so_); GLDS(kt_ + 32 * INC * 2 + koff, ldsA + 4 * SHM_V + so_ + 8192); \
;     GLDS(kt_ + voff, ldsA + so_); GLDS(kt_ + 32 * INC * 2 + voff, ldsA + so_ + 8192); } while (0)
; #define ENDI() do { asm volatile("s_waitcnt vmcnt(0)" ::: "memory"); __syncthreads(); } while (0)
; template <int KS> __device__ __forceinline__ void pv_ks(f32x16* o, int vb, bf16x8 pa) {
;     const s16x4 l0 = tr_read<v_rd_off(0, KS, 0)>(vb), h0 = tr_read<v_rd_off(0, KS, 1)>(vb), l1 = tr_read<v_rd_off(1, KS, 0)>(vb), h1 = tr_read<v_rd_off(1, KS, 1)>(vb);
;     const s16x4 l2 = tr_read<v_rd_off(2, KS, 0)>(vb), h2 = tr_read<v_rd_off(2, KS, 1)>(vb), l3 = tr_read<v_rd_off(3, KS, 0)>(vb), h3 = tr_read<v_rd_off(3, KS, 1)>(vb);
;     ...
;     asm volatile("s_waitcnt lgkmcnt(6)" ::: "memory"); SBAR();
;     o[0] = __builtin_amdgcn_mfma_f32_32x32x16_bf16(pa, PK(l0, h0), o[0], 0, 0, 0);
;     asm volatile("s_waitcnt lgkmcnt(4)" ::: "memory"); SBAR();
;     o[1] = __builtin_amdgcn_mfma_f32_32x32x16_bf16(pa, PK(l1, h1), o[1], 0, 0, 0);
;     asm volatile("s_waitcnt lgkmcnt(2)" ::: "memory"); SBAR();
;     o[2] = __builtin_amdgcn_mfma_f32_32x32x16_bf16(pa, PK(l2, h2), o[2], 0, 0, 0);
;     asm volatile("s_waitcnt lgkmcnt(0)" ::: "memory"); SBAR();
;     o[3] = __builtin_amdgcn_mfma_f32_32x32x16_bf16(pa, PK(l3, h3), o[3], 0, 0, 0);
;     ...
; }
; __device__ __forceinline__ void diff_unit(const DiffArgs& A, int b, int h, int qb, char* lds, int wv) {
;     ...
;         for (int j = 1; j + 1 < NT; j += 2) {
;             STAGE(j + 1);
;             SBAR(); pv_d0(o, vb0 + (j > 1 ? SLOT(j - 2) : 0), pa0, pa1, pa2, pa3);
;             exp_half(pA0); SBAR();
;             BIAS(pB0, pB1, j); qkt<4>(pB0, pB1, K_lds + SLOT(j), qr, r32p, hip, colB0);
;             exp_half(pA1); pack_p(pA0, pA1, l_reg, pa0, pa1, pa2, pa3); SBAR();
;             ENDI();
;             STAGE(j + 2);
;             SBAR(); pv_d0(o, vb0 + SLOT(j - 1), pa0, pa1, pa2, pa3);
;             exp_half(pB0); SBAR();
;             BIAS(pA0, pA1, j + 1); qkt<4>(pA0, pA1, K_lds + SLOT(j + 1), qr, r32p, hip, colB0);
;             exp_half(pB1); pack_p(pB0, pB1, l_reg, pa0, pa1, pa2, pa3); SBAR();
;             ENDI();
.LBB0_228:
	s_add_i32 s56, s56, 0
	s_add_i32 s56, s56, 0x10000
	v_add_u32_e32 v182, s56, v191
	v_add_f32_e32 v187, v190, v64
	ds_read_b128 v[178:181], v182
	ds_read_b128 v[182:185], v182 offset:8192
	s_waitcnt lgkmcnt(0)
	v_mfma_f32_32x32x16_bf16 v[112:127], v[178:181], v[172:175], v[112:127]
	v_mfma_f32_32x32x16_bf16 v[96:111], v[182:185], v[172:175], v[96:111]
	v_add_u32_e32 v182, s56, v198
	ds_read_b128 v[178:181], v182
	ds_read_b128 v[182:185], v182 offset:8192
	s_waitcnt lgkmcnt(0)
	v_mfma_f32_32x32x16_bf16 v[112:127], v[178:181], v[168:171], v[112:127]
	v_exp_f32_e32 v128, v128
	v_exp_f32_e32 v129, v129
	v_exp_f32_e32 v130, v130
	v_mfma_f32_32x32x16_bf16 v[96:111], v[182:185], v[168:171], v[96:111]
	v_add_u32_e32 v182, s56, v199
	ds_read_b128 v[178:181], v182
	ds_read_b128 v[182:185], v182 offset:8192
	v_exp_f32_e32 v131, v131
	v_exp_f32_e32 v135, v135
	v_exp_f32_e32 v196, v141
	v_exp_f32_e32 v197, v142
	v_exp_f32_e32 v202, v143
	s_waitcnt lgkmcnt(0)
	v_mfma_f32_32x32x16_bf16 v[112:127], v[178:181], v[164:167], v[112:127]
	s_add_i32 s53, s53, 2
	v_cvt_pk_bf16_f32 v141, v146, v147
	v_cvt_pk_bf16_f32 v142, v148, v149
	v_cvt_pk_bf16_f32 v143, v150, v151
	v_mfma_f32_32x32x16_bf16 v[96:111], v[182:185], v[164:167], v[96:111]
	v_add_u32_e32 v182, s56, v200
	ds_read_b128 v[178:181], v182
	ds_read_b128 v[182:185], v182 offset:8192
	s_waitcnt lgkmcnt(0)
	v_mfma_f32_32x32x16_bf16 v[112:127], v[178:181], v[160:163], v[112:127]
	v_exp_f32_e32 v178, v132
	v_add_f32_e32 v132, 0, v144
	v_add_f32_e32 v132, v145, v132
	v_add_f32_e32 v132, v146, v132
	v_add_f32_e32 v132, v147, v132
	v_add_f32_e32 v132, v148, v132
	v_add_f32_e32 v132, v149, v132
	v_add_f32_e32 v132, v150, v132
	v_add_f32_e32 v132, v151, v132
	v_add_f32_e32 v132, v152, v132
	v_add_f32_e32 v132, v153, v132
	v_add_f32_e32 v132, v154, v132
	v_add_f32_e32 v132, v155, v132
	v_add_f32_e32 v132, v156, v132
	v_add_f32_e32 v132, v157, v132
	v_add_f32_e32 v132, v158, v132
	v_add_f32_e32 v132, v159, v132
	v_add_f32_e32 v132, v128, v132
	v_exp_f32_e32 v179, v133
	v_add_f32_e32 v132, v129, v132
	v_exp_f32_e32 v180, v134
	v_add_f32_e32 v132, v130, v132
	v_add_f32_e32 v132, v131, v132
	v_exp_f32_e32 v181, v136
	v_add_f32_e32 v132, v178, v132
	v_mfma_f32_32x32x16_bf16 v[96:111], v[182:185], v[160:163], v[96:111]
	v_exp_f32_e32 v182, v137
	v_add_f32_e32 v132, v179, v132
	v_exp_f32_e32 v183, v138
	v_add_f32_e32 v132, v180, v132
	v_exp_f32_e32 v184, v139
	v_add_f32_e32 v132, v135, v132
	v_exp_f32_e32 v185, v140
	v_add_f32_e32 v132, v181, v132
	v_add_f32_e32 v132, v182, v132
	v_add_f32_e32 v132, v183, v132
	v_add_f32_e32 v132, v184, v132
	v_add_f32_e32 v132, v185, v132
	v_add_f32_e32 v132, v196, v132
	v_add_f32_e32 v132, v197, v132
	v_add_f32_e32 v132, v202, v132
	v_add_f32_e32 v190, v187, v132
	v_cvt_pk_bf16_f32 v140, v144, v145
	v_cvt_pk_bf16_f32 v136, v152, v153
	v_cvt_pk_bf16_f32 v137, v154, v155
	v_cvt_pk_bf16_f32 v138, v156, v157
	v_cvt_pk_bf16_f32 v139, v158, v159
	v_cvt_pk_bf16_f32 v132, v128, v129
	v_cvt_pk_bf16_f32 v133, v130, v131
	v_cvt_pk_bf16_f32 v134, v178, v179
	v_cvt_pk_bf16_f32 v135, v180, v135
	v_cvt_pk_bf16_f32 v128, v181, v182
	v_cvt_pk_bf16_f32 v129, v183, v184
	v_cvt_pk_bf16_f32 v130, v185, v196
	v_cvt_pk_bf16_f32 v131, v197, v202
	s_waitcnt vmcnt(0)
	s_add_i32 s54, s54, 0x8000
	s_addk_i32 s55, 0x80
	s_cmp_ge_i32 s53, s62
	v_add_u32_e32 v201, 0xffffff80, v201
	s_waitcnt vmcnt(0)
	s_barrier
	s_cbranch_scc1 .LBB0_238
.LBB0_229:
	s_sub_i32 s56, s55, 64
	s_mul_hi_u32 s57, s56, 0x3800
	s_mulk_i32 s56, 0x3800
	s_add_u32 s58, s18, s56
	s_addc_u32 s59, s19, s57
	s_add_i32 s56, s54, 0xffff8000
	s_and_b32 s56, s56, 0xc000
	s_add_i32 s57, s25, s56
	s_add_u32 vcc_lo, s58, 0x70000
	s_mov_b32 m0, s57
	s_addc_u32 vcc_hi, s59, 0
	global_load_lds_dwordx4 v176, s[58:59]
	s_add_i32 m0, s57, 0x2000
	s_add_i32 s57, s24, s56
	global_load_lds_dwordx4 v176, vcc
	s_mov_b32 m0, s57
	s_nop 0
	global_load_lds_dwordx4 v188, s[58:59]
	s_add_i32 m0, s57, 0x2000
	s_nop 0
	global_load_lds_dwordx4 v188, vcc
	s_add_i32 s57, s54, 0xffff4000
	s_and_b32 s58, s57, 0xc000
	s_xor_b32 s57, s58, 0x8000
	s_cmp_gt_u32 s53, 1
	s_cselect_b32 s57, s57, 0
	v_add_u32_e32 v178, s57, v252
	s_setprio 1
	ds_read_b64_tr_b16 v[144:145], v178 offset:0
	ds_read_b64_tr_b16 v[146:147], v178 offset:0x800
	ds_read_b64_tr_b16 v[148:149], v178 offset:0x200
	ds_read_b64_tr_b16 v[150:151], v178 offset:0xa00
	ds_read_b64_tr_b16 v[152:153], v178 offset:0x400
	ds_read_b64_tr_b16 v[154:155], v178 offset:0xc00
	ds_read_b64_tr_b16 v[156:157], v178 offset:0x600
	ds_read_b64_tr_b16 v[158:159], v178 offset:0xe00
	s_waitcnt lgkmcnt(6)
	v_mfma_f32_32x32x16_bf16 v[48:63], v[140:143], v[144:147], v[48:63]
	ds_read_b64_tr_b16 v[144:145], v178 offset:0x1000
	ds_read_b64_tr_b16 v[146:147], v178 offset:0x1800
	v_exp_f32_e32 v206, v116
	v_exp_f32_e32 v218, v96
	s_waitcnt lgkmcnt(6)
	v_mfma_f32_32x32x16_bf16 v[32:47], v[140:143], v[148:151], v[32:47]
	ds_read_b64_tr_b16 v[148:149], v178 offset:0x1200
	ds_read_b64_tr_b16 v[150:151], v178 offset:0x1a00
	v_exp_f32_e32 v202, v112
	v_exp_f32_e32 v219, v97
	s_waitcnt lgkmcnt(6)
	v_mfma_f32_32x32x16_bf16 v[16:31], v[140:143], v[152:155], v[16:31]
	ds_read_b64_tr_b16 v[152:153], v178 offset:0x1400
	ds_read_b64_tr_b16 v[154:155], v178 offset:0x1c00
	v_exp_f32_e32 v203, v113
	v_exp_f32_e32 v220, v98
	s_waitcnt lgkmcnt(6)
	v_mfma_f32_32x32x16_bf16 v[0:15], v[140:143], v[156:159], v[0:15]
	ds_read_b64_tr_b16 v[156:157], v178 offset:0x1600
	ds_read_b64_tr_b16 v[158:159], v178 offset:0x1e00
	v_exp_f32_e32 v204, v114
	v_exp_f32_e32 v221, v99
	s_waitcnt lgkmcnt(6)
; #define SBAR() __builtin_amdgcn_sched_barrier(0)
; #define STAGE(t) do { const char* kt_ = Pk + (size_t)((t) * KVBLK) * (INC * 2); const int so_ = ((t) & 3) * SHM_K; \
;     GLDS(kt_ + koff, ldsA + 4 * SHM_V + so_); GLDS(kt_ + 32 * INC * 2 + koff, ldsA + 4 * SHM_V + so_ + 8192); \
;     GLDS(kt_ + voff, ldsA + so_); GLDS(kt_ + 32 * INC * 2 + voff, ldsA + so_ + 8192); } while (0)
; template <int KS> __device__ __forceinline__ void pv_ks(f32x16* o, int vb, bf16x8 pa) {
;     const s16x4 l0 = tr_read<v_rd_off(0, KS, 0)>(vb), h0 = tr_read<v_rd_off(0, KS, 1)>(vb), l1 = tr_read<v_rd_off(1, KS, 0)>(vb), h1 = tr_read<v_rd_off(1, KS, 1)>(vb);
;     const s16x4 l2 = tr_read<v_rd_off(2, KS, 0)>(vb), h2 = tr_read<v_rd_off(2, KS, 1)>(vb), l3 = tr_read<v_rd_off(3, KS, 0)>(vb), h3 = tr_read<v_rd_off(3, KS, 1)>(vb);
;     ...
;     asm volatile("s_waitcnt lgkmcnt(6)" ::: "memory"); SBAR();
;     o[0] = __builtin_amdgcn_mfma_f32_32x32x16_bf16(pa, PK(l0, h0), o[0], 0, 0, 0);
;     asm volatile("s_waitcnt lgkmcnt(4)" ::: "memory"); SBAR();
;     o[1] = __builtin_amdgcn_mfma_f32_32x32x16_bf16(pa, PK(l1, h1), o[1], 0, 0, 0);
;     asm volatile("s_waitcnt lgkmcnt(2)" ::: "memory"); SBAR();
;     o[2] = __builtin_amdgcn_mfma_f32_32x32x16_bf16(pa, PK(l2, h2), o[2], 0, 0, 0);
;     asm volatile("s_waitcnt lgkmcnt(0)" ::: "memory"); SBAR();
;     o[3] = __builtin_amdgcn_mfma_f32_32x32x16_bf16(pa, PK(l3, h3), o[3], 0, 0, 0);
;     ...
; }
; __device__ __forceinline__ void pv_d0(f32x16* o, int vb, bf16x8 pa0, bf16x8 pa1, bf16x8 pa2, bf16x8 pa3) {
;     __builtin_amdgcn_s_setprio(1);
;     pv_ks<0>(o, vb, pa0); pv_ks<1>(o, vb, pa1); pv_ks<2>(o, vb, pa2); pv_ks<3>(o, vb, pa3);
;     __builtin_amdgcn_s_setprio(0);
; }
; __device__ __forceinline__ void exp_half(f32x16& p) {
; #pragma unroll
;     for (int r = 0; r < 16; ++r) p[r] = __builtin_amdgcn_exp2f(p[r]);
; }
; __device__ __forceinline__ void diff_unit(const DiffArgs& A, int b, int h, int qb, char* lds, int wv) {
;     ...
;         for (int j = 1; j + 1 < NT; j += 2) {
;             STAGE(j + 1);
;             SBAR(); pv_d0(o, vb0 + (j > 1 ? SLOT(j - 2) : 0), pa0, pa1, pa2, pa3);
;             exp_half(pA0); SBAR();
;             BIAS(pB0, pB1, j); qkt<4>(pB0, pB1, K_lds + SLOT(j), qr, r32p, hip, colB0);
;             exp_half(pA1); pack_p(pA0, pA1, l_reg, pa0, pa1, pa2, pa3); SBAR();
	v_mfma_f32_32x32x16_bf16 v[48:63], v[136:139], v[144:147], v[48:63]
	ds_read_b64_tr_b16 v[144:145], v178 offset:0x2000
	ds_read_b64_tr_b16 v[146:147], v178 offset:0x2800
	v_exp_f32_e32 v205, v115
	v_exp_f32_e32 v222, v100
	s_waitcnt lgkmcnt(6)
	v_mfma_f32_32x32x16_bf16 v[32:47], v[136:139], v[148:151], v[32:47]
	ds_read_b64_tr_b16 v[148:149], v178 offset:0x2200
	ds_read_b64_tr_b16 v[150:151], v178 offset:0x2a00
	v_exp_f32_e32 v207, v117
	v_exp_f32_e32 v223, v101
	s_waitcnt lgkmcnt(6)
	v_mfma_f32_32x32x16_bf16 v[16:31], v[136:139], v[152:155], v[16:31]
	ds_read_b64_tr_b16 v[152:153], v178 offset:0x2400
	ds_read_b64_tr_b16 v[154:155], v178 offset:0x2c00
	v_exp_f32_e32 v208, v118
	v_exp_f32_e32 v237, v102
	s_waitcnt lgkmcnt(6)
	v_mfma_f32_32x32x16_bf16 v[0:15], v[136:139], v[156:159], v[0:15]
	ds_read_b64_tr_b16 v[156:157], v178 offset:0x2600
	ds_read_b64_tr_b16 v[158:159], v178 offset:0x2e00
	v_exp_f32_e32 v209, v119
	v_exp_f32_e32 v238, v103
	s_waitcnt lgkmcnt(6)
	v_mfma_f32_32x32x16_bf16 v[48:63], v[132:135], v[144:147], v[48:63]
	ds_read_b64_tr_b16 v[144:145], v178 offset:0x3000
	ds_read_b64_tr_b16 v[146:147], v178 offset:0x3800
	v_exp_f32_e32 v210, v120
	v_exp_f32_e32 v239, v104
	s_waitcnt lgkmcnt(6)
	v_mfma_f32_32x32x16_bf16 v[32:47], v[132:135], v[148:151], v[32:47]
	ds_read_b64_tr_b16 v[148:149], v178 offset:0x3200
	ds_read_b64_tr_b16 v[150:151], v178 offset:0x3a00
	v_exp_f32_e32 v211, v121
	v_exp_f32_e32 v240, v105
	s_waitcnt lgkmcnt(6)
	v_mfma_f32_32x32x16_bf16 v[16:31], v[132:135], v[152:155], v[16:31]
	ds_read_b64_tr_b16 v[152:153], v178 offset:0x3400
	ds_read_b64_tr_b16 v[154:155], v178 offset:0x3c00
	v_exp_f32_e32 v212, v122
	v_exp_f32_e32 v241, v106
	s_waitcnt lgkmcnt(6)
	v_mfma_f32_32x32x16_bf16 v[0:15], v[132:135], v[156:159], v[0:15]
	ds_read_b64_tr_b16 v[156:157], v178 offset:0x3600
	ds_read_b64_tr_b16 v[158:159], v178 offset:0x3e00
	v_exp_f32_e32 v213, v123
	v_exp_f32_e32 v242, v107
	s_waitcnt lgkmcnt(6)
	v_mfma_f32_32x32x16_bf16 v[48:63], v[128:131], v[144:147], v[48:63]
	v_exp_f32_e32 v214, v124
	v_exp_f32_e32 v243, v108
	s_waitcnt lgkmcnt(4)
	v_mfma_f32_32x32x16_bf16 v[32:47], v[128:131], v[148:151], v[32:47]
	v_exp_f32_e32 v215, v125
	v_exp_f32_e32 v244, v109
	s_waitcnt lgkmcnt(2)
	v_mfma_f32_32x32x16_bf16 v[16:31], v[128:131], v[152:155], v[16:31]
	v_exp_f32_e32 v216, v126
	v_exp_f32_e32 v245, v110
	s_waitcnt lgkmcnt(0)
	v_mfma_f32_32x32x16_bf16 v[0:15], v[128:131], v[156:159], v[0:15]
	v_exp_f32_e32 v217, v127
	v_exp_f32_e32 v246, v111
	s_setprio 0
	v_cvt_f32_i32_e32 v196, v201
	s_add_i32 s57, s63, s55
	s_add_i32 s59, s57, 0xffffff61
	s_cmp_lt_u32 s59, 0xffffffa3
	s_mov_b64 vcc, -1
	s_cbranch_scc1 .LBB0_231
	s_mov_b32 s60, -2.0
	v_add_f32_e32 v197, -1.0, v196
	s_mov_b32 s61, 0xc0400000
	v_pk_add_f32 v[144:145], v[196:197], s[60:61] op_sel_hi:[0,1]
	s_mov_b32 s60, 0xc1000000
	s_mov_b32 s61, 0xc1100000
	v_pk_add_f32 v[146:147], v[196:197], s[60:61] op_sel_hi:[0,1]
	s_mov_b32 s60, 0xc1200000
	s_mov_b32 s61, 0xc1300000
	v_pk_add_f32 v[148:149], v[196:197], s[60:61] op_sel_hi:[0,1]
	s_mov_b32 s60, 0xc1800000
	s_mov_b32 s61, 0xc1880000
	v_pk_add_f32 v[150:151], v[196:197], s[60:61] op_sel_hi:[0,1]
	s_mov_b32 s60, 0xc1900000
	s_mov_b32 s61, 0xc1980000
	v_pk_add_f32 v[152:153], v[196:197], s[60:61] op_sel_hi:[0,1]
	s_mov_b32 s60, 0xc1c00000
	s_mov_b32 s61, 0xc1c80000
	v_pk_add_f32 v[154:155], v[196:197], s[60:61] op_sel_hi:[0,1]
	s_mov_b32 s60, 0xc1d00000
	s_mov_b32 s61, 0xc1d80000
	v_pk_add_f32 v[128:129], v[196:197], s[26:27] op_sel_hi:[1,0]
	v_pk_add_f32 v[130:131], v[144:145], s[26:27] op_sel_hi:[1,0]
	v_pk_add_f32 v[132:133], v[146:147], s[26:27] op_sel_hi:[1,0]
	v_pk_add_f32 v[134:135], v[148:149], s[26:27] op_sel_hi:[1,0]
	v_pk_add_f32 v[136:137], v[150:151], s[26:27] op_sel_hi:[1,0]
	v_pk_add_f32 v[138:139], v[152:153], s[26:27] op_sel_hi:[1,0]
	v_pk_add_f32 v[140:141], v[154:155], s[26:27] op_sel_hi:[1,0]
	v_pk_add_f32 v[178:179], v[196:197], s[60:61] op_sel_hi:[0,1]
	v_and_b32_e32 v129, 0x7fffffff, v129
	v_and_b32_e32 v128, 0x7fffffff, v128
	v_and_b32_e32 v131, 0x7fffffff, v131
	v_and_b32_e32 v130, 0x7fffffff, v130
	v_and_b32_e32 v133, 0x7fffffff, v133
	v_and_b32_e32 v132, 0x7fffffff, v132
	v_and_b32_e32 v135, 0x7fffffff, v135
	v_and_b32_e32 v134, 0x7fffffff, v134
	v_and_b32_e32 v137, 0x7fffffff, v137
	v_and_b32_e32 v136, 0x7fffffff, v136
	v_and_b32_e32 v139, 0x7fffffff, v139
	v_and_b32_e32 v138, 0x7fffffff, v138
	v_and_b32_e32 v141, 0x7fffffff, v141
	v_and_b32_e32 v140, 0x7fffffff, v140
	v_add_f32_e32 v142, 0xc2000000, v178
	v_and_b32_e32 v145, 0x7fffffff, v145
	v_and_b32_e32 v144, 0x7fffffff, v144
	v_and_b32_e32 v147, 0x7fffffff, v147
	v_and_b32_e32 v146, 0x7fffffff, v146
	v_and_b32_e32 v149, 0x7fffffff, v149
	v_and_b32_e32 v148, 0x7fffffff, v148
	v_and_b32_e32 v151, 0x7fffffff, v151
	v_and_b32_e32 v150, 0x7fffffff, v150
	v_and_b32_e32 v153, 0x7fffffff, v153
	v_and_b32_e32 v152, 0x7fffffff, v152
	v_and_b32_e32 v155, 0x7fffffff, v155
	v_and_b32_e32 v154, 0x7fffffff, v154
	v_and_b32_e32 v157, 0x7fffffff, v179
	v_and_b32_e32 v156, 0x7fffffff, v178
	v_and_b32_e32 v180, 0x7fffffff, v196
	v_and_b32_e32 v181, 0x7fffffff, v197
	v_mov_b32_e32 v187, v186
	v_add_f32_e32 v143, 0xc2000000, v179
	v_pk_fma_f32 v[128:129], v[128:129], v[192:193], s[16:17]
	v_pk_fma_f32 v[130:131], v[130:131], v[192:193], s[16:17]
	v_pk_fma_f32 v[132:133], v[132:133], v[192:193], s[16:17]
	v_pk_fma_f32 v[134:135], v[134:135], v[192:193], s[16:17]
	v_pk_fma_f32 v[136:137], v[136:137], v[192:193], s[16:17]
	v_pk_fma_f32 v[138:139], v[138:139], v[192:193], s[16:17]
	v_pk_fma_f32 v[140:141], v[140:141], v[192:193], s[16:17]
	v_fma_f32 v142, |v142|, v186, s16
	v_pk_fma_f32 v[158:159], v[156:157], v[186:187], s[34:35]
	v_pk_fma_f32 v[156:157], v[154:155], v[186:187], s[6:7]
	v_pk_fma_f32 v[154:155], v[152:153], v[186:187], s[8:9]
	v_pk_fma_f32 v[152:153], v[150:151], v[186:187], s[50:51]
	v_pk_fma_f32 v[150:151], v[148:149], v[186:187], s[48:49]
	v_pk_fma_f32 v[148:149], v[146:147], v[186:187], s[46:47]
	v_pk_fma_f32 v[146:147], v[144:145], v[186:187], s[44:45]
	v_pk_fma_f32 v[144:145], v[180:181], v[194:195], s[20:21]
	v_fma_f32 v143, |v143|, v186, s16
	s_mov_b64 vcc, 0

; template <int KS> __device__ __forceinline__ void pv_ks(f32x16* o, int vb, bf16x8 pa) {
;     const s16x4 l0 = tr_read<v_rd_off(0, KS, 0)>(vb), h0 = tr_read<v_rd_off(0, KS, 1)>(vb), l1 = tr_read<v_rd_off(1, KS, 0)>(vb), h1 = tr_read<v_rd_off(1, KS, 1)>(vb);
;     const s16x4 l2 = tr_read<v_rd_off(2, KS, 0)>(vb), h2 = tr_read<v_rd_off(2, KS, 1)>(vb), l3 = tr_read<v_rd_off(3, KS, 0)>(vb), h3 = tr_read<v_rd_off(3, KS, 1)>(vb);
;     ...
;     asm volatile("s_waitcnt lgkmcnt(6)" ::: "memory"); SBAR();
;     o[0] = __builtin_amdgcn_mfma_f32_32x32x16_bf16(pa, PK(l0, h0), o[0], 0, 0, 0);
;     asm volatile("s_waitcnt lgkmcnt(4)" ::: "memory"); SBAR();
;     o[1] = __builtin_amdgcn_mfma_f32_32x32x16_bf16(pa, PK(l1, h1), o[1], 0, 0, 0);
;     asm volatile("s_waitcnt lgkmcnt(2)" ::: "memory"); SBAR();
;     o[2] = __builtin_amdgcn_mfma_f32_32x32x16_bf16(pa, PK(l2, h2), o[2], 0, 0, 0);
;     asm volatile("s_waitcnt lgkmcnt(0)" ::: "memory"); SBAR();
;     o[3] = __builtin_amdgcn_mfma_f32_32x32x16_bf16(pa, PK(l3, h3), o[3], 0, 0, 0);
;     ...
; }
; __device__ __forceinline__ void pv_d0(f32x16* o, int vb, bf16x8 pa0, bf16x8 pa1, bf16x8 pa2, bf16x8 pa3) {
;     __builtin_amdgcn_s_setprio(1);
;     pv_ks<0>(o, vb, pa0); pv_ks<1>(o, vb, pa1); pv_ks<2>(o, vb, pa2); pv_ks<3>(o, vb, pa3);
;     __builtin_amdgcn_s_setprio(0);
; }
; __device__ __forceinline__ void exp_half(f32x16& p) {
; #pragma unroll
;     for (int r = 0; r < 16; ++r) p[r] = __builtin_amdgcn_exp2f(p[r]);
; }
; __device__ __forceinline__ void pack_p(const f32x16& p0, const f32x16& p1, float& l_reg, bf16x8& pa0, bf16x8& pa1, bf16x8& pa2, bf16x8& pa3) {
;     float ps = 0;
; #pragma unroll
;     for (int r = 0; r < 16; ++r) ps += p0[r];
; #pragma unroll
;     for (int r = 0; r < 16; ++r) ps += p1[r];
;     l_reg += ps;
;     ...
;     PK4(p0, 0, pa0); PK4(p0, 8, pa1); PK4(p1, 0, pa2); PK4(p1, 8, pa3);
;     ...
; }
; template <int ND0> __device__ __forceinline__ void qkt(f32x16& p0, f32x16& p1, const char* Ks, const bf16x8* qr, int r32, int hi, int colB0) {
; #pragma unroll
;     for (int d0 = 0; d0 < ND0; ++d0) { const int cb = colB0 + (d0 * 16 + hi * 8) * 2;
;         const bf16x8 b0 = *reinterpret_cast<const bf16x8*>(Ks + KSWZ(r32, cb));
;         const bf16x8 b1 = *reinterpret_cast<const bf16x8*>(Ks + KSWZ(32 + r32, cb));
;         p0 = __builtin_amdgcn_mfma_f32_32x32x16_bf16(b0, qr[d0], p0, 0, 0, 0);
.LBB0_233:
	s_add_i32 s58, s58, 0
	s_add_i32 s58, s58, 0x10000
	v_add_u32_e32 v116, s58, v191
	ds_read_b128 v[112:115], v116
	ds_read_b128 v[116:119], v116 offset:8192
	s_waitcnt lgkmcnt(0)
	v_mfma_f32_32x32x16_bf16 v[144:159], v[112:115], v[172:175], v[144:159]
	v_mfma_f32_32x32x16_bf16 v[128:143], v[116:119], v[172:175], v[128:143]
	v_add_u32_e32 v116, s58, v198
	ds_read_b128 v[112:115], v116
	ds_read_b128 v[116:119], v116 offset:8192
	s_waitcnt lgkmcnt(0)
	v_mfma_f32_32x32x16_bf16 v[144:159], v[112:115], v[168:171], v[144:159]
	v_mfma_f32_32x32x16_bf16 v[128:143], v[116:119], v[168:171], v[128:143]
	v_add_u32_e32 v116, s58, v199
	ds_read_b128 v[112:115], v116
	ds_read_b128 v[116:119], v116 offset:8192
	s_waitcnt lgkmcnt(0)
	v_mfma_f32_32x32x16_bf16 v[144:159], v[112:115], v[164:167], v[144:159]
	v_cvt_pk_bf16_f32 v96, v202, v203
	v_cvt_pk_bf16_f32 v97, v204, v205
	v_cvt_pk_bf16_f32 v98, v206, v207
	v_cvt_pk_bf16_f32 v99, v208, v209
	v_cvt_pk_bf16_f32 v100, v210, v211
	v_cvt_pk_bf16_f32 v101, v212, v213
	v_cvt_pk_bf16_f32 v102, v214, v215
	v_mfma_f32_32x32x16_bf16 v[128:143], v[116:119], v[164:167], v[128:143]
	v_add_u32_e32 v116, s58, v200
	ds_read_b128 v[112:115], v116
	ds_read_b128 v[116:119], v116 offset:8192
	v_cvt_pk_bf16_f32 v103, v216, v217
	v_cvt_pk_bf16_f32 v104, v218, v219
	v_cvt_pk_bf16_f32 v105, v220, v221
	v_cvt_pk_bf16_f32 v106, v222, v223
	v_cvt_pk_bf16_f32 v107, v237, v238
	s_waitcnt lgkmcnt(0)
	v_mfma_f32_32x32x16_bf16 v[144:159], v[112:115], v[160:163], v[144:159]
	v_cvt_pk_bf16_f32 v108, v239, v240
	v_cvt_pk_bf16_f32 v109, v241, v242
	v_cvt_pk_bf16_f32 v110, v243, v244
	v_cvt_pk_bf16_f32 v111, v245, v246
	v_mfma_f32_32x32x16_bf16 v[128:143], v[116:119], v[160:163], v[128:143]
	s_mul_i32 s58, s55, 0x3800
	s_mul_hi_u32 s59, s55, 0x3800
	s_add_u32 s58, s18, s58
	s_addc_u32 s59, s19, s59
	s_add_i32 s60, s54, 0xffffc000
	s_and_b32 s60, s60, 0xc000
	s_add_i32 s61, s25, s60
	s_add_u32 vcc_lo, s58, 0x70000
	s_mov_b32 m0, s61
	s_addc_u32 vcc_hi, s59, 0
	s_waitcnt vmcnt(0)
	s_waitcnt vmcnt(0)
	s_barrier
	global_load_lds_dwordx4 v176, s[58:59]
	s_add_i32 m0, s61, 0x2000
	s_nop 0
	global_load_lds_dwordx4 v176, vcc
	s_add_i32 s100, s24, s60
	s_mov_b32 m0, s100
	s_nop 0
	global_load_lds_dwordx4 v188, s[58:59]
	s_add_i32 m0, s100, 0x2000
	s_nop 0
	global_load_lds_dwordx4 v188, vcc
	s_and_b32 s58, s54, 0xc000
	v_add_u32_e32 v178, s58, v252
	s_setprio 1
	ds_read_b64_tr_b16 v[112:113], v178 offset:0
	ds_read_b64_tr_b16 v[114:115], v178 offset:0x800
	ds_read_b64_tr_b16 v[116:117], v178 offset:0x200
	ds_read_b64_tr_b16 v[118:119], v178 offset:0xa00
	ds_read_b64_tr_b16 v[120:121], v178 offset:0x400
	ds_read_b64_tr_b16 v[122:123], v178 offset:0xc00
	ds_read_b64_tr_b16 v[124:125], v178 offset:0x600
	ds_read_b64_tr_b16 v[126:127], v178 offset:0xe00
	s_waitcnt lgkmcnt(6)
	v_mfma_f32_32x32x16_bf16 v[48:63], v[96:99], v[112:115], v[48:63]
	ds_read_b64_tr_b16 v[112:113], v178 offset:0x1000
	ds_read_b64_tr_b16 v[114:115], v178 offset:0x1800
	v_exp_f32_e32 v144, v144
	v_add_f32_e32 v64, 0, v202
	v_add_f32_e32 v64, v203, v64
	s_waitcnt lgkmcnt(6)
	v_mfma_f32_32x32x16_bf16 v[32:47], v[96:99], v[116:119], v[32:47]
	ds_read_b64_tr_b16 v[116:117], v178 offset:0x1200
	ds_read_b64_tr_b16 v[118:119], v178 offset:0x1a00
	v_exp_f32_e32 v145, v145
	v_add_f32_e32 v64, v204, v64
	v_add_f32_e32 v64, v205, v64
	s_waitcnt lgkmcnt(6)
	v_mfma_f32_32x32x16_bf16 v[16:31], v[96:99], v[120:123], v[16:31]
	ds_read_b64_tr_b16 v[120:121], v178 offset:0x1400
	ds_read_b64_tr_b16 v[122:123], v178 offset:0x1c00
	v_exp_f32_e32 v146, v146
	v_add_f32_e32 v64, v206, v64
	v_add_f32_e32 v64, v207, v64
	s_waitcnt lgkmcnt(6)
	v_mfma_f32_32x32x16_bf16 v[0:15], v[96:99], v[124:127], v[0:15]
	ds_read_b64_tr_b16 v[124:125], v178 offset:0x1600
	ds_read_b64_tr_b16 v[126:127], v178 offset:0x1e00
	v_exp_f32_e32 v147, v147
	v_add_f32_e32 v64, v208, v64
	v_add_f32_e32 v64, v209, v64
	s_waitcnt lgkmcnt(6)
	v_mfma_f32_32x32x16_bf16 v[48:63], v[100:103], v[112:115], v[48:63]
	ds_read_b64_tr_b16 v[112:113], v178 offset:0x2000
	ds_read_b64_tr_b16 v[114:115], v178 offset:0x2800
	v_exp_f32_e32 v148, v148
	v_add_f32_e32 v64, v210, v64
	v_add_f32_e32 v64, v211, v64
	s_waitcnt lgkmcnt(6)
	v_mfma_f32_32x32x16_bf16 v[32:47], v[100:103], v[116:119], v[32:47]
	ds_read_b64_tr_b16 v[116:117], v178 offset:0x2200
	ds_read_b64_tr_b16 v[118:119], v178 offset:0x2a00
	v_exp_f32_e32 v149, v149
	v_add_f32_e32 v64, v212, v64
	v_add_f32_e32 v64, v213, v64
	s_waitcnt lgkmcnt(6)
	v_mfma_f32_32x32x16_bf16 v[16:31], v[100:103], v[120:123], v[16:31]
	ds_read_b64_tr_b16 v[120:121], v178 offset:0x2400
	ds_read_b64_tr_b16 v[122:123], v178 offset:0x2c00
	v_exp_f32_e32 v150, v150
	v_add_f32_e32 v64, v214, v64
	v_add_f32_e32 v64, v215, v64
	s_waitcnt lgkmcnt(6)
	v_mfma_f32_32x32x16_bf16 v[0:15], v[100:103], v[124:127], v[0:15]
	ds_read_b64_tr_b16 v[124:125], v178 offset:0x2600
	ds_read_b64_tr_b16 v[126:127], v178 offset:0x2e00
	v_exp_f32_e32 v151, v151
	v_add_f32_e32 v64, v216, v64
	v_add_f32_e32 v64, v217, v64
	s_waitcnt lgkmcnt(6)
	v_mfma_f32_32x32x16_bf16 v[48:63], v[104:107], v[112:115], v[48:63]
	ds_read_b64_tr_b16 v[112:113], v178 offset:0x3000
	ds_read_b64_tr_b16 v[114:115], v178 offset:0x3800
	v_exp_f32_e32 v152, v152
	v_add_f32_e32 v64, v218, v64
	v_add_f32_e32 v64, v219, v64
	s_waitcnt lgkmcnt(6)
	v_mfma_f32_32x32x16_bf16 v[32:47], v[104:107], v[116:119], v[32:47]
	ds_read_b64_tr_b16 v[116:117], v178 offset:0x3200
	ds_read_b64_tr_b16 v[118:119], v178 offset:0x3a00
	v_exp_f32_e32 v153, v153
	v_add_f32_e32 v64, v220, v64
	v_add_f32_e32 v64, v221, v64
	s_waitcnt lgkmcnt(6)
	v_mfma_f32_32x32x16_bf16 v[16:31], v[104:107], v[120:123], v[16:31]
	ds_read_b64_tr_b16 v[120:121], v178 offset:0x3400
	ds_read_b64_tr_b16 v[122:123], v178 offset:0x3c00
	v_exp_f32_e32 v154, v154
	v_add_f32_e32 v64, v222, v64
	v_add_f32_e32 v64, v223, v64
	s_waitcnt lgkmcnt(6)
	v_mfma_f32_32x32x16_bf16 v[0:15], v[104:107], v[124:127], v[0:15]
	ds_read_b64_tr_b16 v[124:125], v178 offset:0x3600
	ds_read_b64_tr_b16 v[126:127], v178 offset:0x3e00
	v_exp_f32_e32 v155, v155
	v_add_f32_e32 v64, v237, v64
	v_add_f32_e32 v64, v238, v64
	s_waitcnt lgkmcnt(6)
	v_mfma_f32_32x32x16_bf16 v[48:63], v[108:111], v[112:115], v[48:63]
	v_exp_f32_e32 v156, v156
	v_add_f32_e32 v64, v239, v64
	v_add_f32_e32 v64, v240, v64
	s_waitcnt lgkmcnt(4)
	v_mfma_f32_32x32x16_bf16 v[32:47], v[108:111], v[116:119], v[32:47]
	v_exp_f32_e32 v157, v157
	v_add_f32_e32 v64, v241, v64
	v_add_f32_e32 v64, v242, v64
	s_waitcnt lgkmcnt(2)
	v_mfma_f32_32x32x16_bf16 v[16:31], v[108:111], v[120:123], v[16:31]
	v_exp_f32_e32 v158, v158
	v_add_f32_e32 v64, v243, v64
	v_add_f32_e32 v64, v244, v64
	s_waitcnt lgkmcnt(0)
	v_mfma_f32_32x32x16_bf16 v[0:15], v[108:111], v[124:127], v[0:15]
	v_exp_f32_e32 v159, v159
	v_add_f32_e32 v64, v245, v64
	v_add_f32_e32 v64, v246, v64
	s_setprio 0
	v_subrev_u32_e32 v96, 64, v201
	v_cvt_f32_i32_e32 v196, v96
	s_add_i32 s58, s57, 0xffffffa1
	s_cmp_lt_u32 s58, 0xffffffa3
	s_mov_b64 vcc, -1
	s_cbranch_scc1 .LBB0_235
; __device__ __forceinline__ void bias_init(f32x16& p0, f32x16& p1, float base, float nslope2, float nM2, int rel  ) {
;     if (rel <= -63 || rel >= 31) {
;         const float sg = (rel < 0) ? -nslope2 : nslope2, lbv = fmaf(-sg, base, nM2);
; #pragma unroll
;         for (int r = 0; r < 16; ++r) { p0[r] = fmaf((float)((r & 3) + 8 * (r >> 2)), sg, lbv); p1[r] = fmaf((float)((r & 3) + 8 * (r >> 2) + 32), sg, lbv); }
;     } else {
; #pragma unroll
;         for (int r = 0; r < 16; ++r) { const float d = base - (float)((r & 3) + 8 * (r >> 2));
;             p0[r] = fmaf(fabsf(d), nslope2, nM2); p1[r] = fmaf(fabsf(d - 32.f), nslope2, nM2); }
;     }
; }
	s_mov_b32 s58, -2.0
	v_add_f32_e32 v197, -1.0, v196
	s_mov_b32 s59, 0xc0400000
	v_pk_add_f32 v[112:113], v[196:197], s[58:59] op_sel_hi:[0,1]
	s_mov_b32 s58, 0xc1000000
	s_mov_b32 s59, 0xc1100000
	v_pk_add_f32 v[114:115], v[196:197], s[58:59] op_sel_hi:[0,1]
	s_mov_b32 s58, 0xc1200000
	s_mov_b32 s59, 0xc1300000
	v_pk_add_f32 v[116:117], v[196:197], s[58:59] op_sel_hi:[0,1]
	s_mov_b32 s58, 0xc1800000
	s_mov_b32 s59, 0xc1880000
	v_pk_add_f32 v[118:119], v[196:197], s[58:59] op_sel_hi:[0,1]
	s_mov_b32 s58, 0xc1900000
	s_mov_b32 s59, 0xc1980000
	v_pk_add_f32 v[120:121], v[196:197], s[58:59] op_sel_hi:[0,1]
	s_mov_b32 s58, 0xc1c00000
	s_mov_b32 s59, 0xc1c80000
	v_pk_add_f32 v[122:123], v[196:197], s[58:59] op_sel_hi:[0,1]
	s_mov_b32 s58, 0xc1d00000
	s_mov_b32 s59, 0xc1d80000
	v_pk_add_f32 v[96:97], v[196:197], s[26:27] op_sel_hi:[1,0]
	v_pk_add_f32 v[98:99], v[112:113], s[26:27] op_sel_hi:[1,0]
	v_pk_add_f32 v[100:101], v[114:115], s[26:27] op_sel_hi:[1,0]
	v_pk_add_f32 v[102:103], v[116:117], s[26:27] op_sel_hi:[1,0]
	v_pk_add_f32 v[104:105], v[118:119], s[26:27] op_sel_hi:[1,0]
	v_pk_add_f32 v[106:107], v[120:121], s[26:27] op_sel_hi:[1,0]
	v_pk_add_f32 v[108:109], v[122:123], s[26:27] op_sel_hi:[1,0]
	v_pk_add_f32 v[178:179], v[196:197], s[58:59] op_sel_hi:[0,1]
	v_and_b32_e32 v97, 0x7fffffff, v97
	v_and_b32_e32 v96, 0x7fffffff, v96
	v_and_b32_e32 v99, 0x7fffffff, v99
	v_and_b32_e32 v98, 0x7fffffff, v98
	v_and_b32_e32 v101, 0x7fffffff, v101
	v_and_b32_e32 v100, 0x7fffffff, v100
	v_and_b32_e32 v103, 0x7fffffff, v103
	v_and_b32_e32 v102, 0x7fffffff, v102
	v_and_b32_e32 v105, 0x7fffffff, v105
	v_and_b32_e32 v104, 0x7fffffff, v104
	v_and_b32_e32 v107, 0x7fffffff, v107
	v_and_b32_e32 v106, 0x7fffffff, v106
	v_and_b32_e32 v109, 0x7fffffff, v109
	v_and_b32_e32 v108, 0x7fffffff, v108
	v_add_f32_e32 v110, 0xc2000000, v178
	v_and_b32_e32 v113, 0x7fffffff, v113
	v_and_b32_e32 v112, 0x7fffffff, v112
	v_and_b32_e32 v115, 0x7fffffff, v115
	v_and_b32_e32 v114, 0x7fffffff, v114
	v_and_b32_e32 v117, 0x7fffffff, v117
	v_and_b32_e32 v116, 0x7fffffff, v116
	v_and_b32_e32 v119, 0x7fffffff, v119
	v_and_b32_e32 v118, 0x7fffffff, v118
	v_and_b32_e32 v121, 0x7fffffff, v121
	v_and_b32_e32 v120, 0x7fffffff, v120
	v_and_b32_e32 v123, 0x7fffffff, v123
	v_and_b32_e32 v122, 0x7fffffff, v122
	v_and_b32_e32 v125, 0x7fffffff, v179
	v_and_b32_e32 v124, 0x7fffffff, v178
	v_and_b32_e32 v180, 0x7fffffff, v196
	v_and_b32_e32 v181, 0x7fffffff, v197
	v_mov_b32_e32 v187, v186
	v_add_f32_e32 v111, 0xc2000000, v179
	v_pk_fma_f32 v[96:97], v[96:97], v[192:193], s[16:17]
	v_pk_fma_f32 v[98:99], v[98:99], v[192:193], s[16:17]
	v_pk_fma_f32 v[100:101], v[100:101], v[192:193], s[16:17]
	v_pk_fma_f32 v[102:103], v[102:103], v[192:193], s[16:17]
	v_pk_fma_f32 v[104:105], v[104:105], v[192:193], s[16:17]
	v_pk_fma_f32 v[106:107], v[106:107], v[192:193], s[16:17]
	v_pk_fma_f32 v[108:109], v[108:109], v[192:193], s[16:17]
	v_fma_f32 v110, |v110|, v186, s16
	v_pk_fma_f32 v[126:127], v[124:125], v[186:187], s[34:35]
	v_pk_fma_f32 v[124:125], v[122:123], v[186:187], s[6:7]
	v_pk_fma_f32 v[122:123], v[120:121], v[186:187], s[8:9]
	v_pk_fma_f32 v[120:121], v[118:119], v[186:187], s[50:51]
	v_pk_fma_f32 v[118:119], v[116:117], v[186:187], s[48:49]
	v_pk_fma_f32 v[116:117], v[114:115], v[186:187], s[46:47]
	v_pk_fma_f32 v[114:115], v[112:113], v[186:187], s[44:45]
	v_pk_fma_f32 v[112:113], v[180:181], v[194:195], s[20:21]
	v_fma_f32 v111, |v111|, v186, s16
	s_mov_b64 vcc, 0

; template <int KS> __device__ __forceinline__ void pv_ks(f32x16* o, int vb, bf16x8 pa) {
;     const s16x4 l0 = tr_read<v_rd_off(0, KS, 0)>(vb), h0 = tr_read<v_rd_off(0, KS, 1)>(vb), l1 = tr_read<v_rd_off(1, KS, 0)>(vb), h1 = tr_read<v_rd_off(1, KS, 1)>(vb);
;     const s16x4 l2 = tr_read<v_rd_off(2, KS, 0)>(vb), h2 = tr_read<v_rd_off(2, KS, 1)>(vb), l3 = tr_read<v_rd_off(3, KS, 0)>(vb), h3 = tr_read<v_rd_off(3, KS, 1)>(vb);
;     ...
;     asm volatile("s_waitcnt lgkmcnt(6)" ::: "memory"); SBAR();
;     o[0] = __builtin_amdgcn_mfma_f32_32x32x16_bf16(pa, PK(l0, h0), o[0], 0, 0, 0);
;     asm volatile("s_waitcnt lgkmcnt(4)" ::: "memory"); SBAR();
;     o[1] = __builtin_amdgcn_mfma_f32_32x32x16_bf16(pa, PK(l1, h1), o[1], 0, 0, 0);
;     asm volatile("s_waitcnt lgkmcnt(2)" ::: "memory"); SBAR();
;     o[2] = __builtin_amdgcn_mfma_f32_32x32x16_bf16(pa, PK(l2, h2), o[2], 0, 0, 0);
;     asm volatile("s_waitcnt lgkmcnt(0)" ::: "memory"); SBAR();
;     o[3] = __builtin_amdgcn_mfma_f32_32x32x16_bf16(pa, PK(l3, h3), o[3], 0, 0, 0);
;     ...
; }
; __device__ __forceinline__ void pv_d0(f32x16* o, int vb, bf16x8 pa0, bf16x8 pa1, bf16x8 pa2, bf16x8 pa3) {
;     __builtin_amdgcn_s_setprio(1);
;     pv_ks<0>(o, vb, pa0); pv_ks<1>(o, vb, pa1); pv_ks<2>(o, vb, pa2); pv_ks<3>(o, vb, pa3);
;     __builtin_amdgcn_s_setprio(0);
; }
; __device__ __forceinline__ void exp_half(f32x16& p) {
; #pragma unroll
;     for (int r = 0; r < 16; ++r) p[r] = __builtin_amdgcn_exp2f(p[r]);
; }
; __device__ __forceinline__ void pack_p(const f32x16& p0, const f32x16& p1, float& l_reg, bf16x8& pa0, bf16x8& pa1, bf16x8& pa2, bf16x8& pa3) {
;     float ps = 0;
; #pragma unroll
;     for (int r = 0; r < 16; ++r) ps += p0[r];
; #pragma unroll
;     for (int r = 0; r < 16; ++r) ps += p1[r];
;     l_reg += ps;
;     ...
;     PK4(p0, 0, pa0); PK4(p0, 8, pa1); PK4(p1, 0, pa2); PK4(p1, 8, pa3);
;     ...
; }
; template <int ND0> __device__ __forceinline__ void qkt(f32x16& p0, f32x16& p1, const char* Ks, const bf16x8* qr, int r32, int hi, int colB0) {
; #pragma unroll
;     for (int d0 = 0; d0 < ND0; ++d0) { const int cb = colB0 + (d0 * 16 + hi * 8) * 2;
;         const bf16x8 b0 = *reinterpret_cast<const bf16x8*>(Ks + KSWZ(r32, cb));
;         const bf16x8 b1 = *reinterpret_cast<const bf16x8*>(Ks + KSWZ(32 + r32, cb));
;         p0 = __builtin_amdgcn_mfma_f32_32x32x16_bf16(b0, qr[d0], p0, 0, 0, 0);
.LBB0_247:
	v_exp_f32_e32 v195, v100
	v_exp_f32_e32 v100, v106
	v_add_f32_e32 v106, 0, v129
	v_add_f32_e32 v106, v132, v106
	v_add_f32_e32 v106, v140, v106
	v_add_f32_e32 v106, v138, v106
	v_add_f32_e32 v106, v148, v106
	v_add_f32_e32 v106, v146, v106
	v_add_f32_e32 v106, v156, v106
	v_add_f32_e32 v106, v154, v106
	v_add_f32_e32 v106, v158, v106
	v_add_f32_e32 v106, v130, v106
	v_add_f32_e32 v106, v136, v106
	v_add_f32_e32 v106, v134, v106
	v_add_f32_e32 v106, v144, v106
	v_add_f32_e32 v106, v142, v106
	v_add_f32_e32 v106, v152, v106
	s_add_i32 s55, s55, 0
	v_add_f32_e32 v106, v150, v106
	s_add_i32 s55, s55, 0x10000
	v_exp_f32_e32 v202, v101
	v_exp_f32_e32 v101, v107
	v_add_f32_e32 v106, v141, v106
	v_add_u32_e32 v107, s55, v131
	v_exp_f32_e32 v187, v97
	v_exp_f32_e32 v194, v99
	v_exp_f32_e32 v203, v102
	v_exp_f32_e32 v204, v103
	v_exp_f32_e32 v97, v104
	v_exp_f32_e32 v99, v105
	v_exp_f32_e32 v102, v108
	v_exp_f32_e32 v103, v109
	v_exp_f32_e32 v104, v110
	v_exp_f32_e32 v105, v111
	v_add_f32_e32 v106, v143, v106
	ds_read_b128 v[108:111], v107
	ds_read_b128 v[140:143], v107 offset:8192
	s_waitcnt lgkmcnt(0)
	v_mfma_f32_32x32x16_bf16 v[112:127], v[108:111], v[172:175], v[112:127]
	v_add_u32_e32 v107, s55, v133
	v_exp_f32_e32 v96, v96
	v_exp_f32_e32 v98, v98
	v_add_f32_e32 v106, v145, v106
	v_exp_f32_e32 v129, v85
	v_add_f32_e32 v106, v147, v106
	v_exp_f32_e32 v130, v86
	v_mfma_f32_32x32x16_bf16 v[64:79], v[140:143], v[172:175], v[64:79]
	ds_read_b128 v[108:111], v107
	ds_read_b128 v[140:143], v107 offset:8192
	v_add_u32_e32 v107, s55, v135
	v_add_f32_e32 v106, v149, v106
	v_exp_f32_e32 v132, v87
	v_add_f32_e32 v106, v151, v106
	v_exp_f32_e32 v134, v88
	v_add_f32_e32 v106, v153, v106
	s_waitcnt lgkmcnt(0)
	v_mfma_f32_32x32x16_bf16 v[112:127], v[108:111], v[168:171], v[112:127]
	v_exp_f32_e32 v136, v89
	v_add_f32_e32 v106, v155, v106
	v_exp_f32_e32 v138, v90
	v_add_f32_e32 v106, v157, v106
	v_add_f32_e32 v106, v159, v106
	v_add_f32_e32 v106, v196, v106
	v_add_f32_e32 v106, v197, v106
	v_mfma_f32_32x32x16_bf16 v[64:79], v[140:143], v[168:171], v[64:79]
	ds_read_b128 v[108:111], v107
	ds_read_b128 v[140:143], v107 offset:8192
	v_add_u32_e32 v107, s55, v137
	v_add_f32_e32 v106, v198, v106
	v_exp_f32_e32 v95, v95
	v_add_f32_e32 v106, v199, v106
	v_add_f32_e32 v106, v200, v106
	v_add_f32_e32 v106, v201, v106
	s_waitcnt lgkmcnt(0)
	v_mfma_f32_32x32x16_bf16 v[112:127], v[108:111], v[164:167], v[112:127]
	v_add_f32_e32 v106, v128, v106
	s_add_i32 s52, s52, 2
	v_cvt_pk_bf16_f32 v85, v100, v101
	v_cvt_pk_bf16_f32 v86, v102, v103
	v_cvt_pk_bf16_f32 v87, v104, v105
	v_mfma_f32_32x32x16_bf16 v[64:79], v[140:143], v[164:167], v[64:79]
	ds_read_b128 v[108:111], v107
	ds_read_b128 v[140:143], v107 offset:8192
	v_exp_f32_e32 v107, v80
	v_add_f32_e32 v80, 0, v96
	v_add_f32_e32 v80, v187, v80
	v_add_f32_e32 v80, v98, v80
	v_add_f32_e32 v80, v194, v80
	v_add_f32_e32 v80, v195, v80
	v_add_f32_e32 v80, v202, v80
	v_add_f32_e32 v80, v203, v80
	v_add_f32_e32 v80, v204, v80
	v_add_f32_e32 v80, v97, v80
	v_add_f32_e32 v80, v99, v80
	v_add_f32_e32 v80, v100, v80
	v_add_f32_e32 v80, v101, v80
	v_add_f32_e32 v80, v102, v80
	s_waitcnt lgkmcnt(0)
	v_mfma_f32_32x32x16_bf16 v[112:127], v[108:111], v[160:163], v[112:127]
	v_exp_f32_e32 v108, v81
	v_add_f32_e32 v80, v103, v80
	v_exp_f32_e32 v109, v82
	v_add_f32_e32 v80, v104, v80
	v_exp_f32_e32 v110, v83
	v_add_f32_e32 v80, v105, v80
	v_exp_f32_e32 v111, v84
	v_add_f32_e32 v80, v107, v80
	v_add_f32_e32 v80, v108, v80
	v_add_f32_e32 v80, v109, v80
	v_add_f32_e32 v80, v110, v80
	v_add_f32_e32 v80, v111, v80
	v_add_f32_e32 v80, v129, v80
	v_add_f32_e32 v80, v130, v80
	v_mfma_f32_32x32x16_bf16 v[64:79], v[140:143], v[160:163], v[64:79]
	v_exp_f32_e32 v140, v91
	v_add_f32_e32 v80, v132, v80
	v_exp_f32_e32 v141, v92
	v_add_f32_e32 v80, v134, v80
	v_exp_f32_e32 v142, v93
	v_add_f32_e32 v80, v136, v80
	v_exp_f32_e32 v143, v94
	v_add_f32_e32 v80, v138, v80
	v_add_f32_e32 v80, v140, v80
	v_add_f32_e32 v80, v141, v80
	v_add_f32_e32 v80, v142, v80
	v_add_f32_e32 v80, v143, v80
	v_add_f32_e32 v80, v95, v80
	v_add_f32_e32 v128, v106, v80
	v_cvt_pk_bf16_f32 v80, v96, v187
	v_cvt_pk_bf16_f32 v81, v98, v194
	v_cvt_pk_bf16_f32 v82, v195, v202
	v_cvt_pk_bf16_f32 v83, v203, v204
	v_cvt_pk_bf16_f32 v84, v97, v99
	v_cvt_pk_bf16_f32 v88, v107, v108
	v_cvt_pk_bf16_f32 v89, v109, v110
	v_cvt_pk_bf16_f32 v90, v111, v129
	v_cvt_pk_bf16_f32 v91, v130, v132
	v_cvt_pk_bf16_f32 v92, v134, v136
	v_cvt_pk_bf16_f32 v93, v138, v140
	v_cvt_pk_bf16_f32 v94, v141, v142
	v_cvt_pk_bf16_f32 v95, v143, v95
	v_add_u32_e32 v129, s56, v252
	s_setprio 1
	ds_read_b64_tr_b16 v[96:97], v129 offset:0
	ds_read_b64_tr_b16 v[98:99], v129 offset:0x800
	ds_read_b64_tr_b16 v[100:101], v129 offset:0x200
	ds_read_b64_tr_b16 v[102:103], v129 offset:0xa00
	ds_read_b64_tr_b16 v[104:105], v129 offset:0x400
	ds_read_b64_tr_b16 v[106:107], v129 offset:0xc00
	ds_read_b64_tr_b16 v[108:109], v129 offset:0x600
	ds_read_b64_tr_b16 v[110:111], v129 offset:0xe00
	s_waitcnt lgkmcnt(6)
	v_mfma_f32_32x32x16_bf16 v[48:63], v[80:83], v[96:99], v[48:63]
	ds_read_b64_tr_b16 v[96:97], v129 offset:0x1000
	ds_read_b64_tr_b16 v[98:99], v129 offset:0x1800
	v_exp_f32_e32 v132, v113
	s_waitcnt lgkmcnt(6)
	v_mfma_f32_32x32x16_bf16 v[32:47], v[80:83], v[100:103], v[32:47]
	ds_read_b64_tr_b16 v[100:101], v129 offset:0x1200
	ds_read_b64_tr_b16 v[102:103], v129 offset:0x1a00
	v_exp_f32_e32 v140, v114
	s_waitcnt lgkmcnt(6)
	v_mfma_f32_32x32x16_bf16 v[16:31], v[80:83], v[104:107], v[16:31]
	ds_read_b64_tr_b16 v[104:105], v129 offset:0x1400
	ds_read_b64_tr_b16 v[106:107], v129 offset:0x1c00
	v_exp_f32_e32 v138, v115
	s_waitcnt lgkmcnt(6)
; #define SBAR() __builtin_amdgcn_sched_barrier(0)
; #define STAGE(t) do { const char* kt_ = Pk + (size_t)((t) * KVBLK) * (INC * 2); const int so_ = ((t) & 3) * SHM_K; \
;     GLDS(kt_ + koff, ldsA + 4 * SHM_V + so_); GLDS(kt_ + 32 * INC * 2 + koff, ldsA + 4 * SHM_V + so_ + 8192); \
;     GLDS(kt_ + voff, ldsA + so_); GLDS(kt_ + 32 * INC * 2 + voff, ldsA + so_ + 8192); } while (0)
; #define ENDI() do { asm volatile("s_waitcnt vmcnt(0)" ::: "memory"); __syncthreads(); } while (0)
; #define BIAS(P0, P1, t) bias_init(P0, P1, (float)(iposk - (t) * KVBLK), nslope2, nM2, relw + (t) * KVBLK)
; template <int KS> __device__ __forceinline__ void pv_ks(f32x16* o, int vb, bf16x8 pa) {
;     const s16x4 l0 = tr_read<v_rd_off(0, KS, 0)>(vb), h0 = tr_read<v_rd_off(0, KS, 1)>(vb), l1 = tr_read<v_rd_off(1, KS, 0)>(vb), h1 = tr_read<v_rd_off(1, KS, 1)>(vb);
;     const s16x4 l2 = tr_read<v_rd_off(2, KS, 0)>(vb), h2 = tr_read<v_rd_off(2, KS, 1)>(vb), l3 = tr_read<v_rd_off(3, KS, 0)>(vb), h3 = tr_read<v_rd_off(3, KS, 1)>(vb);
;     ...
;     asm volatile("s_waitcnt lgkmcnt(6)" ::: "memory"); SBAR();
;     o[0] = __builtin_amdgcn_mfma_f32_32x32x16_bf16(pa, PK(l0, h0), o[0], 0, 0, 0);
;     asm volatile("s_waitcnt lgkmcnt(4)" ::: "memory"); SBAR();
;     o[1] = __builtin_amdgcn_mfma_f32_32x32x16_bf16(pa, PK(l1, h1), o[1], 0, 0, 0);
;     asm volatile("s_waitcnt lgkmcnt(2)" ::: "memory"); SBAR();
;     o[2] = __builtin_amdgcn_mfma_f32_32x32x16_bf16(pa, PK(l2, h2), o[2], 0, 0, 0);
;     asm volatile("s_waitcnt lgkmcnt(0)" ::: "memory"); SBAR();
;     o[3] = __builtin_amdgcn_mfma_f32_32x32x16_bf16(pa, PK(l3, h3), o[3], 0, 0, 0);
;     ...
; }
; __device__ __forceinline__ void pv_d0(f32x16* o, int vb, bf16x8 pa0, bf16x8 pa1, bf16x8 pa2, bf16x8 pa3) {
;     __builtin_amdgcn_s_setprio(1);
;     pv_ks<0>(o, vb, pa0); pv_ks<1>(o, vb, pa1); pv_ks<2>(o, vb, pa2); pv_ks<3>(o, vb, pa3);
;     __builtin_amdgcn_s_setprio(0);
; }
; __device__ __forceinline__ void exp_half(f32x16& p) {
; #pragma unroll
;     for (int r = 0; r < 16; ++r) p[r] = __builtin_amdgcn_exp2f(p[r]);
; }
; __device__ __forceinline__ void diff_unit(const DiffArgs& A, int b, int h, int qb, char* lds, int wv) {
;     ...
;             pv_d0(o, vb0 + SLOT(j - 1), pa0, pa1, pa2, pa3); exp_half(pB0);
;             ENDI();
;             STAGE(j + 2);
;             SBAR(); BIAS(pA0, pA1, j + 1); qkt<4>(pA0, pA1, K_lds + SLOT(j + 1), qr, r32p, hip, colB0);
	v_mfma_f32_32x32x16_bf16 v[0:15], v[80:83], v[108:111], v[0:15]
	ds_read_b64_tr_b16 v[108:109], v129 offset:0x1600
	ds_read_b64_tr_b16 v[110:111], v129 offset:0x1e00
	v_exp_f32_e32 v148, v116
	s_waitcnt lgkmcnt(6)
	v_mfma_f32_32x32x16_bf16 v[48:63], v[84:87], v[96:99], v[48:63]
	ds_read_b64_tr_b16 v[96:97], v129 offset:0x2000
	ds_read_b64_tr_b16 v[98:99], v129 offset:0x2800
	v_exp_f32_e32 v146, v117
	s_waitcnt lgkmcnt(6)
	v_mfma_f32_32x32x16_bf16 v[32:47], v[84:87], v[100:103], v[32:47]
	ds_read_b64_tr_b16 v[100:101], v129 offset:0x2200
	ds_read_b64_tr_b16 v[102:103], v129 offset:0x2a00
	v_exp_f32_e32 v156, v118
	s_waitcnt lgkmcnt(6)
	v_mfma_f32_32x32x16_bf16 v[16:31], v[84:87], v[104:107], v[16:31]
	ds_read_b64_tr_b16 v[104:105], v129 offset:0x2400
	ds_read_b64_tr_b16 v[106:107], v129 offset:0x2c00
	v_exp_f32_e32 v154, v119
	s_waitcnt lgkmcnt(6)
	v_mfma_f32_32x32x16_bf16 v[0:15], v[84:87], v[108:111], v[0:15]
	ds_read_b64_tr_b16 v[108:109], v129 offset:0x2600
	ds_read_b64_tr_b16 v[110:111], v129 offset:0x2e00
	v_exp_f32_e32 v158, v120
	s_waitcnt lgkmcnt(6)
	v_mfma_f32_32x32x16_bf16 v[48:63], v[88:91], v[96:99], v[48:63]
	ds_read_b64_tr_b16 v[96:97], v129 offset:0x3000
	ds_read_b64_tr_b16 v[98:99], v129 offset:0x3800
	v_exp_f32_e32 v130, v121
	s_waitcnt lgkmcnt(6)
	v_mfma_f32_32x32x16_bf16 v[32:47], v[88:91], v[100:103], v[32:47]
	ds_read_b64_tr_b16 v[100:101], v129 offset:0x3200
	ds_read_b64_tr_b16 v[102:103], v129 offset:0x3a00
	v_exp_f32_e32 v136, v122
	s_waitcnt lgkmcnt(6)
	v_mfma_f32_32x32x16_bf16 v[16:31], v[88:91], v[104:107], v[16:31]
	ds_read_b64_tr_b16 v[104:105], v129 offset:0x3400
	ds_read_b64_tr_b16 v[106:107], v129 offset:0x3c00
	v_exp_f32_e32 v134, v123
	s_waitcnt lgkmcnt(6)
	v_mfma_f32_32x32x16_bf16 v[0:15], v[88:91], v[108:111], v[0:15]
	ds_read_b64_tr_b16 v[108:109], v129 offset:0x3600
	ds_read_b64_tr_b16 v[110:111], v129 offset:0x3e00
	v_exp_f32_e32 v144, v124
	s_waitcnt lgkmcnt(6)
	v_mfma_f32_32x32x16_bf16 v[48:63], v[92:95], v[96:99], v[48:63]
	v_exp_f32_e32 v142, v125
	s_waitcnt lgkmcnt(4)
	v_mfma_f32_32x32x16_bf16 v[32:47], v[92:95], v[100:103], v[32:47]
	v_exp_f32_e32 v152, v126
	s_waitcnt lgkmcnt(2)
	v_mfma_f32_32x32x16_bf16 v[16:31], v[92:95], v[104:107], v[16:31]
	v_exp_f32_e32 v150, v127
	s_waitcnt lgkmcnt(0)
	v_mfma_f32_32x32x16_bf16 v[0:15], v[92:95], v[108:111], v[0:15]
	v_exp_f32_e32 v129, v112
	s_setprio 0
	s_waitcnt vmcnt(0)
	s_add_i32 s53, s53, 0x8000
	s_addk_i32 s54, 0x80
	s_cmp_ge_i32 s52, s62
	v_add_u32_e32 v139, 0xffffff80, v139
	s_waitcnt vmcnt(0)
	s_barrier
	s_cbranch_scc1 .LBB0_257
.LBB0_248:
	s_sub_i32 s55, s54, 64
	s_mul_hi_u32 s57, s55, 0x3800
	s_mulk_i32 s55, 0x3800
	s_add_u32 s56, s18, s55
	s_addc_u32 s57, s19, s57
	s_add_i32 s55, s53, 0xffff8000
	s_and_b32 s55, s55, 0xc000
	s_add_i32 vcc_lo, s25, s55
	s_add_u32 s58, s56, 0x70000
	s_mov_b32 m0, vcc_lo
	s_addc_u32 s59, s57, 0
	global_load_lds_dwordx4 v176, s[56:57]
	s_add_i32 m0, vcc_lo, 0x2000
	s_nop 0
	global_load_lds_dwordx4 v176, s[58:59]
	s_add_i32 s100, s24, s55
	s_mov_b32 m0, s100
	s_nop 0
	global_load_lds_dwordx4 v188, s[56:57]
	s_add_i32 m0, s100, 0x2000
	s_nop 0
	global_load_lds_dwordx4 v188, s[58:59]
	v_cvt_f32_i32_e32 v112, v139
	s_add_i32 s57, s63, s54
	s_add_i32 s56, s57, 0xffffff61
	s_cmp_lt_u32 s56, 0xffffffa3
	s_mov_b64 vcc, -1
	s_cbranch_scc1 .LBB0_250
	s_mov_b32 s58, -2.0
	v_add_f32_e32 v113, -1.0, v112
	s_mov_b32 s59, 0xc0400000
	v_pk_add_f32 v[96:97], v[112:113], s[58:59] op_sel_hi:[0,1]
	s_mov_b32 s58, 0xc1000000
	s_mov_b32 s59, 0xc1100000
	v_pk_add_f32 v[98:99], v[112:113], s[58:59] op_sel_hi:[0,1]
	s_mov_b32 s58, 0xc1200000
	s_mov_b32 s59, 0xc1300000
	v_pk_add_f32 v[100:101], v[112:113], s[58:59] op_sel_hi:[0,1]
	s_mov_b32 s58, 0xc1800000
	s_mov_b32 s59, 0xc1880000
	v_pk_add_f32 v[102:103], v[112:113], s[58:59] op_sel_hi:[0,1]
	s_mov_b32 s58, 0xc1900000
	s_mov_b32 s59, 0xc1980000
	v_pk_add_f32 v[104:105], v[112:113], s[58:59] op_sel_hi:[0,1]
	s_mov_b32 s58, 0xc1c00000
	s_mov_b32 s59, 0xc1c80000
	v_pk_add_f32 v[106:107], v[112:113], s[58:59] op_sel_hi:[0,1]
	s_mov_b32 s58, 0xc1d00000
	s_mov_b32 s59, 0xc1d80000
	v_pk_add_f32 v[80:81], v[112:113], s[26:27] op_sel_hi:[1,0]
	v_pk_add_f32 v[82:83], v[96:97], s[26:27] op_sel_hi:[1,0]
	v_pk_add_f32 v[84:85], v[98:99], s[26:27] op_sel_hi:[1,0]
	v_pk_add_f32 v[86:87], v[100:101], s[26:27] op_sel_hi:[1,0]
	v_pk_add_f32 v[88:89], v[102:103], s[26:27] op_sel_hi:[1,0]
	v_pk_add_f32 v[90:91], v[104:105], s[26:27] op_sel_hi:[1,0]
	v_pk_add_f32 v[92:93], v[106:107], s[26:27] op_sel_hi:[1,0]
	v_pk_add_f32 v[114:115], v[112:113], s[58:59] op_sel_hi:[0,1]
	v_and_b32_e32 v81, 0x7fffffff, v81
	v_and_b32_e32 v80, 0x7fffffff, v80
	v_and_b32_e32 v83, 0x7fffffff, v83
	v_and_b32_e32 v82, 0x7fffffff, v82
	v_and_b32_e32 v85, 0x7fffffff, v85
	v_and_b32_e32 v84, 0x7fffffff, v84
	v_and_b32_e32 v87, 0x7fffffff, v87
	v_and_b32_e32 v86, 0x7fffffff, v86
	v_and_b32_e32 v89, 0x7fffffff, v89
	v_and_b32_e32 v88, 0x7fffffff, v88
	v_and_b32_e32 v91, 0x7fffffff, v91
	v_and_b32_e32 v90, 0x7fffffff, v90
	v_and_b32_e32 v93, 0x7fffffff, v93
	v_and_b32_e32 v92, 0x7fffffff, v92
	v_add_f32_e32 v94, 0xc2000000, v114
	v_and_b32_e32 v97, 0x7fffffff, v97
	v_and_b32_e32 v96, 0x7fffffff, v96
	v_and_b32_e32 v99, 0x7fffffff, v99
	v_and_b32_e32 v98, 0x7fffffff, v98
	v_and_b32_e32 v101, 0x7fffffff, v101
	v_and_b32_e32 v100, 0x7fffffff, v100
	v_and_b32_e32 v103, 0x7fffffff, v103
	v_and_b32_e32 v102, 0x7fffffff, v102
	v_and_b32_e32 v105, 0x7fffffff, v105
	v_and_b32_e32 v104, 0x7fffffff, v104
	v_and_b32_e32 v107, 0x7fffffff, v107
	v_and_b32_e32 v106, 0x7fffffff, v106
	v_and_b32_e32 v109, 0x7fffffff, v115
	v_and_b32_e32 v108, 0x7fffffff, v114
	v_and_b32_e32 v116, 0x7fffffff, v112
	v_and_b32_e32 v117, 0x7fffffff, v113
	v_mov_b32_e32 v187, v186
	v_add_f32_e32 v95, 0xc2000000, v115
	v_pk_fma_f32 v[80:81], v[80:81], v[190:191], s[16:17]
	v_pk_fma_f32 v[82:83], v[82:83], v[190:191], s[16:17]
	v_pk_fma_f32 v[84:85], v[84:85], v[190:191], s[16:17]
	v_pk_fma_f32 v[86:87], v[86:87], v[190:191], s[16:17]
	v_pk_fma_f32 v[88:89], v[88:89], v[190:191], s[16:17]
	v_pk_fma_f32 v[90:91], v[90:91], v[190:191], s[16:17]
	v_pk_fma_f32 v[92:93], v[92:93], v[190:191], s[16:17]
	v_fma_f32 v94, |v94|, v186, s16
	v_pk_fma_f32 v[110:111], v[108:109], v[186:187], s[50:51]
	v_pk_fma_f32 v[108:109], v[106:107], v[186:187], s[48:49]
	v_pk_fma_f32 v[106:107], v[104:105], v[186:187], s[46:47]
	v_pk_fma_f32 v[104:105], v[102:103], v[186:187], s[44:45]
	v_pk_fma_f32 v[102:103], v[100:101], v[186:187], s[34:35]
	v_pk_fma_f32 v[100:101], v[98:99], v[186:187], s[20:21]
	v_pk_fma_f32 v[98:99], v[96:97], v[186:187], s[8:9]
	v_pk_fma_f32 v[96:97], v[116:117], v[192:193], s[6:7]
	v_fma_f32 v95, |v95|, v186, s16
	s_mov_b64 vcc, 0

; template <int KS> __device__ __forceinline__ void pv_ks(f32x16* o, int vb, bf16x8 pa) {
;     const s16x4 l0 = tr_read<v_rd_off(0, KS, 0)>(vb), h0 = tr_read<v_rd_off(0, KS, 1)>(vb), l1 = tr_read<v_rd_off(1, KS, 0)>(vb), h1 = tr_read<v_rd_off(1, KS, 1)>(vb);
;     const s16x4 l2 = tr_read<v_rd_off(2, KS, 0)>(vb), h2 = tr_read<v_rd_off(2, KS, 1)>(vb), l3 = tr_read<v_rd_off(3, KS, 0)>(vb), h3 = tr_read<v_rd_off(3, KS, 1)>(vb);
;     ...
;     asm volatile("s_waitcnt lgkmcnt(6)" ::: "memory"); SBAR();
;     o[0] = __builtin_amdgcn_mfma_f32_32x32x16_bf16(pa, PK(l0, h0), o[0], 0, 0, 0);
;     asm volatile("s_waitcnt lgkmcnt(4)" ::: "memory"); SBAR();
;     o[1] = __builtin_amdgcn_mfma_f32_32x32x16_bf16(pa, PK(l1, h1), o[1], 0, 0, 0);
;     asm volatile("s_waitcnt lgkmcnt(2)" ::: "memory"); SBAR();
;     o[2] = __builtin_amdgcn_mfma_f32_32x32x16_bf16(pa, PK(l2, h2), o[2], 0, 0, 0);
;     asm volatile("s_waitcnt lgkmcnt(0)" ::: "memory"); SBAR();
;     o[3] = __builtin_amdgcn_mfma_f32_32x32x16_bf16(pa, PK(l3, h3), o[3], 0, 0, 0);
;     ...
; }
; __device__ __forceinline__ void pv_d0(f32x16* o, int vb, bf16x8 pa0, bf16x8 pa1, bf16x8 pa2, bf16x8 pa3) {
;     __builtin_amdgcn_s_setprio(1);
;     pv_ks<0>(o, vb, pa0); pv_ks<1>(o, vb, pa1); pv_ks<2>(o, vb, pa2); pv_ks<3>(o, vb, pa3);
;     __builtin_amdgcn_s_setprio(0);
; }
; __device__ __forceinline__ void exp_half(f32x16& p) {
; #pragma unroll
;     for (int r = 0; r < 16; ++r) p[r] = __builtin_amdgcn_exp2f(p[r]);
; }
; __device__ __forceinline__ void pack_p(const f32x16& p0, const f32x16& p1, float& l_reg, bf16x8& pa0, bf16x8& pa1, bf16x8& pa2, bf16x8& pa3) {
;     float ps = 0;
; #pragma unroll
;     for (int r = 0; r < 16; ++r) ps += p0[r];
; #pragma unroll
;     for (int r = 0; r < 16; ++r) ps += p1[r];
;     l_reg += ps;
;     ...
;     PK4(p0, 0, pa0); PK4(p0, 8, pa1); PK4(p1, 0, pa2); PK4(p1, 8, pa3);
;     ...
; }
; template <int ND0> __device__ __forceinline__ void qkt(f32x16& p0, f32x16& p1, const char* Ks, const bf16x8* qr, int r32, int hi, int colB0) {
; #pragma unroll
;     for (int d0 = 0; d0 < ND0; ++d0) { const int cb = colB0 + (d0 * 16 + hi * 8) * 2;
;         const bf16x8 b0 = *reinterpret_cast<const bf16x8*>(Ks + KSWZ(r32, cb));
;         const bf16x8 b1 = *reinterpret_cast<const bf16x8*>(Ks + KSWZ(32 + r32, cb));
;         p0 = __builtin_amdgcn_mfma_f32_32x32x16_bf16(b0, qr[d0], p0, 0, 0, 0);
.LBB0_252:
	s_add_i32 s56, s53, 0xffff4000
	s_and_b32 s56, s56, 0xc000
	s_add_i32 s58, s56, 0
	s_add_i32 s58, s58, 0x10000
	v_add_u32_e32 v116, s58, v131
	ds_read_b128 v[112:115], v116
	ds_read_b128 v[116:119], v116 offset:8192
	v_exp_f32_e32 v141, v64
	v_exp_f32_e32 v143, v65
	v_exp_f32_e32 v145, v66
	s_waitcnt lgkmcnt(0)
	v_mfma_f32_32x32x16_bf16 v[96:111], v[112:115], v[172:175], v[96:111]
	v_exp_f32_e32 v147, v67
	v_exp_f32_e32 v149, v68
	v_exp_f32_e32 v151, v69
	v_exp_f32_e32 v153, v70
	v_exp_f32_e32 v155, v71
	v_exp_f32_e32 v157, v72
	v_exp_f32_e32 v159, v73
	v_mfma_f32_32x32x16_bf16 v[80:95], v[116:119], v[172:175], v[80:95]
	v_add_u32_e32 v116, s58, v133
	ds_read_b128 v[112:115], v116
	ds_read_b128 v[116:119], v116 offset:8192
	v_exp_f32_e32 v196, v74
	v_exp_f32_e32 v197, v75
	v_exp_f32_e32 v198, v76
	v_exp_f32_e32 v199, v77
	v_exp_f32_e32 v200, v78
	s_waitcnt lgkmcnt(0)
	v_mfma_f32_32x32x16_bf16 v[96:111], v[112:115], v[168:171], v[96:111]
	v_exp_f32_e32 v201, v79
	v_cvt_pk_bf16_f32 v64, v129, v132
	v_cvt_pk_bf16_f32 v65, v140, v138
	v_cvt_pk_bf16_f32 v66, v148, v146
	v_cvt_pk_bf16_f32 v67, v156, v154
	v_cvt_pk_bf16_f32 v68, v158, v130
	v_cvt_pk_bf16_f32 v69, v136, v134
	v_mfma_f32_32x32x16_bf16 v[80:95], v[116:119], v[168:171], v[80:95]
	v_add_u32_e32 v116, s58, v135
	ds_read_b128 v[112:115], v116
	ds_read_b128 v[116:119], v116 offset:8192
	v_cvt_pk_bf16_f32 v70, v144, v142
	v_cvt_pk_bf16_f32 v71, v152, v150
	v_cvt_pk_bf16_f32 v72, v141, v143
	v_cvt_pk_bf16_f32 v73, v145, v147
	v_cvt_pk_bf16_f32 v74, v149, v151
	s_waitcnt lgkmcnt(0)
	v_mfma_f32_32x32x16_bf16 v[96:111], v[112:115], v[164:167], v[96:111]
	v_cvt_pk_bf16_f32 v75, v153, v155
	v_cvt_pk_bf16_f32 v76, v157, v159
	v_cvt_pk_bf16_f32 v77, v196, v197
	v_cvt_pk_bf16_f32 v78, v198, v199
	v_cvt_pk_bf16_f32 v79, v200, v201
	v_mfma_f32_32x32x16_bf16 v[80:95], v[116:119], v[164:167], v[80:95]
	v_add_u32_e32 v116, s58, v137
	ds_read_b128 v[112:115], v116
	ds_read_b128 v[116:119], v116 offset:8192
	s_waitcnt lgkmcnt(0)
	v_mfma_f32_32x32x16_bf16 v[96:111], v[112:115], v[160:163], v[96:111]
	v_mfma_f32_32x32x16_bf16 v[80:95], v[116:119], v[160:163], v[80:95]
	s_and_b32 s58, s53, 0xc000
	v_add_u32_e32 v178, s58, v252
	s_setprio 1
	ds_read_b64_tr_b16 v[112:113], v178 offset:0
	ds_read_b64_tr_b16 v[114:115], v178 offset:0x800
	ds_read_b64_tr_b16 v[116:117], v178 offset:0x200
	ds_read_b64_tr_b16 v[118:119], v178 offset:0xa00
	ds_read_b64_tr_b16 v[120:121], v178 offset:0x400
	ds_read_b64_tr_b16 v[122:123], v178 offset:0xc00
	ds_read_b64_tr_b16 v[124:125], v178 offset:0x600
	ds_read_b64_tr_b16 v[126:127], v178 offset:0xe00
	s_waitcnt lgkmcnt(6)
	v_mfma_f32_32x32x16_bf16 v[48:63], v[64:67], v[112:115], v[48:63]
	ds_read_b64_tr_b16 v[112:113], v178 offset:0x1000
	ds_read_b64_tr_b16 v[114:115], v178 offset:0x1800
	s_waitcnt lgkmcnt(6)
	v_mfma_f32_32x32x16_bf16 v[32:47], v[64:67], v[116:119], v[32:47]
	ds_read_b64_tr_b16 v[116:117], v178 offset:0x1200
	ds_read_b64_tr_b16 v[118:119], v178 offset:0x1a00
	s_waitcnt lgkmcnt(6)
	v_mfma_f32_32x32x16_bf16 v[16:31], v[64:67], v[120:123], v[16:31]
	ds_read_b64_tr_b16 v[120:121], v178 offset:0x1400
	ds_read_b64_tr_b16 v[122:123], v178 offset:0x1c00
	s_waitcnt lgkmcnt(6)
	v_mfma_f32_32x32x16_bf16 v[0:15], v[64:67], v[124:127], v[0:15]
	ds_read_b64_tr_b16 v[124:125], v178 offset:0x1600
	ds_read_b64_tr_b16 v[126:127], v178 offset:0x1e00
	s_waitcnt lgkmcnt(6)
	v_mfma_f32_32x32x16_bf16 v[48:63], v[68:71], v[112:115], v[48:63]
	ds_read_b64_tr_b16 v[112:113], v178 offset:0x2000
	ds_read_b64_tr_b16 v[114:115], v178 offset:0x2800
	s_waitcnt lgkmcnt(6)
	v_mfma_f32_32x32x16_bf16 v[32:47], v[68:71], v[116:119], v[32:47]
	ds_read_b64_tr_b16 v[116:117], v178 offset:0x2200
	ds_read_b64_tr_b16 v[118:119], v178 offset:0x2a00
	s_waitcnt lgkmcnt(6)
	v_mfma_f32_32x32x16_bf16 v[16:31], v[68:71], v[120:123], v[16:31]
	ds_read_b64_tr_b16 v[120:121], v178 offset:0x2400
	ds_read_b64_tr_b16 v[122:123], v178 offset:0x2c00
	s_waitcnt lgkmcnt(6)
	v_mfma_f32_32x32x16_bf16 v[0:15], v[68:71], v[124:127], v[0:15]
	ds_read_b64_tr_b16 v[124:125], v178 offset:0x2600
	ds_read_b64_tr_b16 v[126:127], v178 offset:0x2e00
	s_waitcnt lgkmcnt(6)
	v_mfma_f32_32x32x16_bf16 v[48:63], v[72:75], v[112:115], v[48:63]
	ds_read_b64_tr_b16 v[112:113], v178 offset:0x3000
	ds_read_b64_tr_b16 v[114:115], v178 offset:0x3800
	s_waitcnt lgkmcnt(6)
	v_mfma_f32_32x32x16_bf16 v[32:47], v[72:75], v[116:119], v[32:47]
	ds_read_b64_tr_b16 v[116:117], v178 offset:0x3200
	ds_read_b64_tr_b16 v[118:119], v178 offset:0x3a00
	s_waitcnt lgkmcnt(6)
	v_mfma_f32_32x32x16_bf16 v[16:31], v[72:75], v[120:123], v[16:31]
	ds_read_b64_tr_b16 v[120:121], v178 offset:0x3400
	ds_read_b64_tr_b16 v[122:123], v178 offset:0x3c00
	s_waitcnt lgkmcnt(6)
	v_mfma_f32_32x32x16_bf16 v[0:15], v[72:75], v[124:127], v[0:15]
	ds_read_b64_tr_b16 v[124:125], v178 offset:0x3600
	ds_read_b64_tr_b16 v[126:127], v178 offset:0x3e00
	s_waitcnt lgkmcnt(6)
	v_mfma_f32_32x32x16_bf16 v[48:63], v[76:79], v[112:115], v[48:63]
	s_waitcnt lgkmcnt(4)
	v_mfma_f32_32x32x16_bf16 v[32:47], v[76:79], v[116:119], v[32:47]
	s_waitcnt lgkmcnt(2)
	v_mfma_f32_32x32x16_bf16 v[16:31], v[76:79], v[120:123], v[16:31]
	s_waitcnt lgkmcnt(0)
	v_mfma_f32_32x32x16_bf16 v[0:15], v[76:79], v[124:127], v[0:15]
	s_setprio 0
	s_mul_i32 s58, s54, 0x3800
	s_mul_hi_u32 s59, s54, 0x3800
	s_add_u32 s58, s18, s58
	s_addc_u32 s59, s19, s59
	s_add_i32 vcc_lo, s53, 0xffffc000
	s_and_b32 s60, vcc_lo, 0xc000
	s_add_i32 s61, s25, s60
	s_add_u32 vcc_lo, s58, 0x70000
	s_mov_b32 m0, s61
	s_addc_u32 vcc_hi, s59, 0
	s_waitcnt vmcnt(0)
	s_waitcnt vmcnt(0)
	s_barrier
; __device__ __forceinline__ void bias_init(f32x16& p0, f32x16& p1, float base, float nslope2, float nM2, int rel  ) {
;     if (rel <= -63 || rel >= 31) {
;         const float sg = (rel < 0) ? -nslope2 : nslope2, lbv = fmaf(-sg, base, nM2);
; #pragma unroll
;         for (int r = 0; r < 16; ++r) { p0[r] = fmaf((float)((r & 3) + 8 * (r >> 2)), sg, lbv); p1[r] = fmaf((float)((r & 3) + 8 * (r >> 2) + 32), sg, lbv); }
	global_load_lds_dwordx4 v176, s[58:59]
	s_add_i32 m0, s61, 0x2000
	s_nop 0
	global_load_lds_dwordx4 v176, vcc
	s_add_i32 s100, s24, s60
	s_mov_b32 m0, s100
	s_nop 0
	global_load_lds_dwordx4 v188, s[58:59]
	s_add_i32 m0, s100, 0x2000
	s_nop 0
	global_load_lds_dwordx4 v188, vcc
	v_subrev_u32_e32 v64, 64, v139
	v_cvt_f32_i32_e32 v194, v64
	s_add_i32 s58, s57, 0xffffffa1
	s_cmp_lt_u32 s58, 0xffffffa3
	s_mov_b64 vcc, -1
	s_cbranch_scc1 .LBB0_254
	s_mov_b32 s58, -2.0
	v_add_f32_e32 v195, -1.0, v194
	s_mov_b32 s59, 0xc0400000
	v_pk_add_f32 v[112:113], v[194:195], s[58:59] op_sel_hi:[0,1]
	s_mov_b32 s58, 0xc1000000
	s_mov_b32 s59, 0xc1100000
	v_pk_add_f32 v[114:115], v[194:195], s[58:59] op_sel_hi:[0,1]
	s_mov_b32 s58, 0xc1200000
	s_mov_b32 s59, 0xc1300000
	v_pk_add_f32 v[116:117], v[194:195], s[58:59] op_sel_hi:[0,1]
	s_mov_b32 s58, 0xc1800000
	s_mov_b32 s59, 0xc1880000
	v_pk_add_f32 v[118:119], v[194:195], s[58:59] op_sel_hi:[0,1]
	s_mov_b32 s58, 0xc1900000
	s_mov_b32 s59, 0xc1980000
	v_pk_add_f32 v[120:121], v[194:195], s[58:59] op_sel_hi:[0,1]
	s_mov_b32 s58, 0xc1c00000
	s_mov_b32 s59, 0xc1c80000
	v_pk_add_f32 v[122:123], v[194:195], s[58:59] op_sel_hi:[0,1]
	s_mov_b32 s58, 0xc1d00000
	s_mov_b32 s59, 0xc1d80000
	v_pk_add_f32 v[64:65], v[194:195], s[26:27] op_sel_hi:[1,0]
	v_pk_add_f32 v[66:67], v[112:113], s[26:27] op_sel_hi:[1,0]
	v_pk_add_f32 v[68:69], v[114:115], s[26:27] op_sel_hi:[1,0]
	v_pk_add_f32 v[70:71], v[116:117], s[26:27] op_sel_hi:[1,0]
	v_pk_add_f32 v[72:73], v[118:119], s[26:27] op_sel_hi:[1,0]
	v_pk_add_f32 v[74:75], v[120:121], s[26:27] op_sel_hi:[1,0]
	v_pk_add_f32 v[76:77], v[122:123], s[26:27] op_sel_hi:[1,0]
	v_pk_add_f32 v[178:179], v[194:195], s[58:59] op_sel_hi:[0,1]
	v_and_b32_e32 v65, 0x7fffffff, v65
	v_and_b32_e32 v64, 0x7fffffff, v64
	v_and_b32_e32 v67, 0x7fffffff, v67
	v_and_b32_e32 v66, 0x7fffffff, v66
	v_and_b32_e32 v69, 0x7fffffff, v69
	v_and_b32_e32 v68, 0x7fffffff, v68
	v_and_b32_e32 v71, 0x7fffffff, v71
	v_and_b32_e32 v70, 0x7fffffff, v70
	v_and_b32_e32 v73, 0x7fffffff, v73
	v_and_b32_e32 v72, 0x7fffffff, v72
	v_and_b32_e32 v75, 0x7fffffff, v75
	v_and_b32_e32 v74, 0x7fffffff, v74
	v_and_b32_e32 v77, 0x7fffffff, v77
	v_and_b32_e32 v76, 0x7fffffff, v76
	v_add_f32_e32 v78, 0xc2000000, v178
	v_and_b32_e32 v113, 0x7fffffff, v113
	v_and_b32_e32 v112, 0x7fffffff, v112
	v_and_b32_e32 v115, 0x7fffffff, v115
	v_and_b32_e32 v114, 0x7fffffff, v114
	v_and_b32_e32 v117, 0x7fffffff, v117
	v_and_b32_e32 v116, 0x7fffffff, v116
	v_and_b32_e32 v119, 0x7fffffff, v119
	v_and_b32_e32 v118, 0x7fffffff, v118
	v_and_b32_e32 v121, 0x7fffffff, v121
	v_and_b32_e32 v120, 0x7fffffff, v120
	v_and_b32_e32 v123, 0x7fffffff, v123
	v_and_b32_e32 v122, 0x7fffffff, v122
	v_and_b32_e32 v125, 0x7fffffff, v179
	v_and_b32_e32 v124, 0x7fffffff, v178
	v_and_b32_e32 v180, 0x7fffffff, v194
	v_and_b32_e32 v181, 0x7fffffff, v195
	v_mov_b32_e32 v187, v186
	v_add_f32_e32 v79, 0xc2000000, v179
	v_pk_fma_f32 v[64:65], v[64:65], v[190:191], s[16:17]
	v_pk_fma_f32 v[66:67], v[66:67], v[190:191], s[16:17]
	v_pk_fma_f32 v[68:69], v[68:69], v[190:191], s[16:17]
	v_pk_fma_f32 v[70:71], v[70:71], v[190:191], s[16:17]
	v_pk_fma_f32 v[72:73], v[72:73], v[190:191], s[16:17]
	v_pk_fma_f32 v[74:75], v[74:75], v[190:191], s[16:17]
	v_pk_fma_f32 v[76:77], v[76:77], v[190:191], s[16:17]
	v_fma_f32 v78, |v78|, v186, s16
	v_pk_fma_f32 v[126:127], v[124:125], v[186:187], s[50:51]
	v_pk_fma_f32 v[124:125], v[122:123], v[186:187], s[48:49]
	v_pk_fma_f32 v[122:123], v[120:121], v[186:187], s[46:47]
	v_pk_fma_f32 v[120:121], v[118:119], v[186:187], s[44:45]
	v_pk_fma_f32 v[118:119], v[116:117], v[186:187], s[34:35]
	v_pk_fma_f32 v[116:117], v[114:115], v[186:187], s[20:21]
	v_pk_fma_f32 v[114:115], v[112:113], v[186:187], s[8:9]
	v_pk_fma_f32 v[112:113], v[180:181], v[192:193], s[6:7]
	v_fma_f32 v79, |v79|, v186, s16
	s_mov_b64 vcc, 0
